# stick-breaking unit deal: wave 4's third unit in running-stream workgroups is now a short early-query-block unit (position swap), rest unchanged
# speedup vs baseline: 1.0028x; 1.0028x over previous
; __device__ __forceinline__ void sb_queue(const Args& a, int l, unsigned* qc, unsigned lo, unsigned hi_, LAS unsigned char* wl, int lane) {
;     ...
;     for (int k = 0; k < 3; ++k) {
;         int u; unsigned p = 0u; bool slow = false;
;         if (k == 0) { if (wv == 0 && v < 128u) slow = true; else p = 2048u + v * 8u + (unsigned)wv; }
;         else if (k == 1) p = v * 8u + (unsigned)wv;
;         else { if (wv != 4 || v >= 128u) break; p = 2048u + v * 8u; }
;         if (slow) u = 4096 + (int)v;
;         else if (p < 3904u) u = (int)(p / 122u) * 128 + 6 + (int)(p % 122u);
;         else { const unsigned x = p - 3904u; u = (int)(x / 6u) * 128 + (int)(x % 6u); }
.LBB0_864:
	s_sub_i32 s6, s19, 0x800
	s_cmp_lt_u32 s6, 0x400
	s_cbranch_scc0 .Lsbq_chkB
	s_and_b32 s7, s6, 7
	s_cbranch_scc1 .Lsbq_done
	s_lshr_b32 s6, s6, 3
	s_add_i32 s19, s6, 0xf40
	s_branch .Lsbq_done
.Lsbq_chkB:
	s_sub_i32 s6, s19, 0xf40
	s_cmp_lt_u32 s6, 0x80
	s_cbranch_scc0 .Lsbq_done
	s_lshl_b32 s6, s6, 3
	s_add_i32 s19, s6, 0x800
